# FFN-up and projection GEMM epilogues: RMS partial sums prefetched once per tile (quarter-row per lane + exact-order permlane reduction) instead of 8 serialized load groups
# speedup vs baseline: 1.0523x; 1.0037x over previous
.LBB0_397:
	v_lshl_add_u32 v140, s41, 8, v144
	v_ashrrev_i32_e32 v141, 31, v140
	v_lshlrev_b64 v[164:165], 6, v[140:141]
	v_lshl_add_u64 v[164:165], s[66:67], 0, v[164:165]
	v_and_b32_e32 v166, 48, v197
	v_mov_b32_e32 v167, 0
	v_lshl_add_u64 v[164:165], v[164:165], 0, v[166:167]
	s_mov_b64 s[10:11], 0x2000
	v_lshl_add_u64 v[166:167], v[164:165], 0, s[10:11]
	global_load_dwordx4 v[204:207], v[164:165], off
	global_load_dwordx4 v[208:211], v[164:165], off offset:1024
	global_load_dwordx4 v[212:215], v[164:165], off offset:2048
	global_load_dwordx4 v[216:219], v[164:165], off offset:3072
	global_load_dwordx4 v[220:223], v[166:167], off
	global_load_dwordx4 v[224:227], v[166:167], off offset:1024
	global_load_dwordx4 v[228:231], v[166:167], off offset:2048
	global_load_dwordx4 v[232:235], v[166:167], off offset:3072
	s_add_i32 s15, s40, -6
	s_sub_i32 s10, s40, 18
	s_cmp_lt_u32 s10, 12
	s_cselect_b32 s17, 3, 0
	s_cmp_lt_u32 s15, 6
	s_cselect_b64 s[10:11], -1, 0
	s_and_b64 s[22:23], s[10:11], exec
	s_cselect_b32 s17, 2, s17
	s_cmp_lt_u32 s15, -3
	s_cselect_b32 s15, s17, 1
	s_cmp_gt_i32 s15, 2
	s_mov_b64 s[22:23], -1
	s_waitcnt vmcnt(0)
	v_add_f32_e32 v204, v204, v205
	v_add_f32_e32 v206, v206, v207
	v_add_f32_e32 v204, v204, v206
	v_mov_b32_e32 v205, v204
	s_nop 1
	v_permlane16_swap_b32_e32 v204, v205
	v_add_f32_e32 v204, v204, v205
	v_mov_b32_e32 v205, v204
	s_nop 1
	v_permlane32_swap_b32_e32 v204, v205
	v_add_f32_e32 v141, v204, v205
	v_fmamk_f32 v141, v141, 0x3a800000, v161
	v_mul_f32_e32 v142, 0x4b800000, v141
	v_cmp_gt_f32_e32 vcc, s62, v141
	s_nop 1
	v_cndmask_b32_e32 v141, v141, v142, vcc
	v_rsq_f32_e32 v141, v141
	s_nop 0
	v_mul_f32_e32 v142, 0x45800000, v141
	v_cndmask_b32_e32 v141, v141, v142, vcc
	v_mul_f32_e32 v142, 0x3e38aa3b, v141
	v_cndmask_b32_e64 v142, v141, v142, s[10:11]
	v_pk_mul_f32 v[128:129], v[128:129], v[142:143] op_sel_hi:[1,0]
	v_pk_mul_f32 v[126:127], v[126:127], v[142:143] op_sel_hi:[1,0]
	v_pk_mul_f32 v[124:125], v[124:125], v[142:143] op_sel_hi:[1,0]
	v_pk_mul_f32 v[122:123], v[122:123], v[142:143] op_sel_hi:[1,0]
	s_cbranch_scc0 .LBB0_399
	v_mul_f32_e32 v143, 0xbfb8aa3b, v122
	v_exp_f32_e32 v143, v143
	v_mul_f32_e32 v163, 0xbfb8aa3b, v127
	v_exp_f32_e32 v164, v163
	v_mul_f32_e32 v163, 0xbfb8aa3b, v123
	v_exp_f32_e32 v165, v163
	v_add_f32_e32 v143, 1.0, v143
	v_rcp_f32_e32 v163, v143
	v_add_f32_e32 v143, 1.0, v164
	v_rcp_f32_e32 v164, v143
	v_add_f32_e32 v143, 1.0, v165
	v_mul_f32_e32 v165, 0xbfb8aa3b, v128
	v_exp_f32_e32 v166, v165
	v_mul_f32_e32 v165, 0xbfb8aa3b, v124
	v_exp_f32_e32 v167, v165
	v_rcp_f32_e32 v165, v143
	v_add_f32_e32 v143, 1.0, v166
	v_rcp_f32_e32 v166, v143
	v_add_f32_e32 v143, 1.0, v167
	v_mul_f32_e32 v167, 0xbfb8aa3b, v129
	v_mul_f32_e32 v141, 0xbfb8aa3b, v126
	v_exp_f32_e32 v168, v167
	v_mul_f32_e32 v167, 0xbfb8aa3b, v125
	v_exp_f32_e32 v141, v141
	v_exp_f32_e32 v170, v167
	v_rcp_f32_e32 v167, v143
	v_add_f32_e32 v143, 1.0, v168
	v_add_f32_e32 v141, 1.0, v141
	v_rcp_f32_e32 v169, v143
	v_add_f32_e32 v143, 1.0, v170
	v_rcp_f32_e32 v141, v141
	v_rcp_f32_e32 v168, v143
	s_mov_b64 s[22:23], 0

.LBB0_409:
	v_cvt_pk_bf16_f32 v114, v126, v128
	v_cvt_pk_bf16_f32 v115, v141, v163
	v_cvt_pk_bf16_f32 v116, v127, v129
	v_cvt_pk_bf16_f32 v117, v142, v143
	global_store_dwordx4 v[124:125], v[114:117], off offset:256
	s_cmp_gt_i32 s15, 2
	s_mov_b64 s[22:23], -1
	v_or_b32_e32 v114, 16, v140
	v_ashrrev_i32_e32 v115, 31, v114
	v_add_f32_e32 v208, v208, v209
	v_add_f32_e32 v210, v210, v211
	v_add_f32_e32 v208, v208, v210
	v_mov_b32_e32 v209, v208
	s_nop 1
	v_permlane16_swap_b32_e32 v208, v209
	v_add_f32_e32 v208, v208, v209
	v_mov_b32_e32 v209, v208
	s_nop 1
	v_permlane32_swap_b32_e32 v208, v209
	v_add_f32_e32 v115, v208, v209
	v_fmamk_f32 v115, v115, 0x3a800000, v161
	v_mul_f32_e32 v116, 0x4b800000, v115
	v_cmp_gt_f32_e32 vcc, s62, v115
	s_nop 1
	v_cndmask_b32_e32 v115, v115, v116, vcc
	v_rsq_f32_e32 v115, v115
	s_nop 0
	v_mul_f32_e32 v116, 0x45800000, v115
	v_cndmask_b32_e32 v115, v115, v116, vcc
	v_mul_f32_e32 v116, 0x3e38aa3b, v115
	v_cndmask_b32_e64 v116, v115, v116, s[10:11]
	v_pk_mul_f32 v[112:113], v[112:113], v[116:117] op_sel_hi:[1,0]
	v_pk_mul_f32 v[110:111], v[110:111], v[116:117] op_sel_hi:[1,0]
	v_pk_mul_f32 v[108:109], v[108:109], v[116:117] op_sel_hi:[1,0]
	v_pk_mul_f32 v[106:107], v[106:107], v[116:117] op_sel_hi:[1,0]
	s_cbranch_scc0 .LBB0_411
	v_mul_f32_e32 v117, 0xbfb8aa3b, v106
	v_exp_f32_e32 v117, v117
	v_mul_f32_e32 v118, 0xbfb8aa3b, v111
	v_exp_f32_e32 v119, v118
	v_mul_f32_e32 v118, 0xbfb8aa3b, v107
	v_exp_f32_e32 v120, v118
	v_add_f32_e32 v117, 1.0, v117
	v_rcp_f32_e32 v118, v117
	v_add_f32_e32 v117, 1.0, v119
	v_rcp_f32_e32 v119, v117
	v_add_f32_e32 v117, 1.0, v120
	v_mul_f32_e32 v120, 0xbfb8aa3b, v112
	v_exp_f32_e32 v121, v120
	v_mul_f32_e32 v120, 0xbfb8aa3b, v108
	v_exp_f32_e32 v124, v120
	v_rcp_f32_e32 v120, v117
	v_add_f32_e32 v117, 1.0, v121
	v_rcp_f32_e32 v121, v117
	v_add_f32_e32 v117, 1.0, v124
	v_mul_f32_e32 v124, 0xbfb8aa3b, v113
	v_mul_f32_e32 v115, 0xbfb8aa3b, v110
	v_exp_f32_e32 v125, v124
	v_mul_f32_e32 v124, 0xbfb8aa3b, v109
	v_exp_f32_e32 v115, v115
	v_exp_f32_e32 v127, v124
	v_rcp_f32_e32 v124, v117
	v_add_f32_e32 v117, 1.0, v125
	v_add_f32_e32 v115, 1.0, v115
	v_rcp_f32_e32 v126, v117
	v_add_f32_e32 v117, 1.0, v127
	v_rcp_f32_e32 v115, v115
	v_rcp_f32_e32 v125, v117
	s_mov_b64 s[22:23], 0

.LBB0_421:
	v_cvt_pk_bf16_f32 v98, v108, v110
	v_cvt_pk_bf16_f32 v99, v112, v115
	v_cvt_pk_bf16_f32 v100, v109, v111
	v_cvt_pk_bf16_f32 v101, v113, v114
	global_store_dwordx4 v[106:107], v[98:101], off offset:256
	s_cmp_gt_i32 s15, 2
	s_mov_b64 s[22:23], -1
	v_or_b32_e32 v98, 32, v140
	v_ashrrev_i32_e32 v99, 31, v98
	v_add_f32_e32 v212, v212, v213
	v_add_f32_e32 v214, v214, v215
	v_add_f32_e32 v212, v212, v214
	v_mov_b32_e32 v213, v212
	s_nop 1
	v_permlane16_swap_b32_e32 v212, v213
	v_add_f32_e32 v212, v212, v213
	v_mov_b32_e32 v213, v212
	s_nop 1
	v_permlane32_swap_b32_e32 v212, v213
	v_add_f32_e32 v99, v212, v213
	v_fmamk_f32 v99, v99, 0x3a800000, v161
	v_mul_f32_e32 v100, 0x4b800000, v99
	v_cmp_gt_f32_e32 vcc, s62, v99
	s_nop 1
	v_cndmask_b32_e32 v99, v99, v100, vcc
	v_rsq_f32_e32 v99, v99
	s_nop 0
	v_mul_f32_e32 v100, 0x45800000, v99
	v_cndmask_b32_e32 v99, v99, v100, vcc
	v_mul_f32_e32 v100, 0x3e38aa3b, v99
	v_cndmask_b32_e64 v100, v99, v100, s[10:11]
	v_pk_mul_f32 v[96:97], v[96:97], v[100:101] op_sel_hi:[1,0]
	v_pk_mul_f32 v[94:95], v[94:95], v[100:101] op_sel_hi:[1,0]
	v_pk_mul_f32 v[92:93], v[92:93], v[100:101] op_sel_hi:[1,0]
	v_pk_mul_f32 v[90:91], v[90:91], v[100:101] op_sel_hi:[1,0]
	s_cbranch_scc0 .LBB0_423
	v_mul_f32_e32 v101, 0xbfb8aa3b, v90
	v_exp_f32_e32 v101, v101
	v_mul_f32_e32 v102, 0xbfb8aa3b, v95
	v_exp_f32_e32 v103, v102
	v_mul_f32_e32 v102, 0xbfb8aa3b, v91
	v_exp_f32_e32 v104, v102
	v_add_f32_e32 v101, 1.0, v101
	v_rcp_f32_e32 v102, v101
	v_add_f32_e32 v101, 1.0, v103
	v_rcp_f32_e32 v103, v101
	v_add_f32_e32 v101, 1.0, v104
	v_mul_f32_e32 v104, 0xbfb8aa3b, v96
	v_exp_f32_e32 v105, v104
	v_mul_f32_e32 v104, 0xbfb8aa3b, v92
	v_exp_f32_e32 v106, v104
	v_rcp_f32_e32 v104, v101
	v_add_f32_e32 v101, 1.0, v105
	v_rcp_f32_e32 v105, v101
	v_add_f32_e32 v101, 1.0, v106
	v_mul_f32_e32 v106, 0xbfb8aa3b, v97
	v_mul_f32_e32 v99, 0xbfb8aa3b, v94
	v_exp_f32_e32 v107, v106
	v_mul_f32_e32 v106, 0xbfb8aa3b, v93
	v_exp_f32_e32 v99, v99
	v_exp_f32_e32 v109, v106
	v_rcp_f32_e32 v106, v101
	v_add_f32_e32 v101, 1.0, v107
	v_add_f32_e32 v99, 1.0, v99
	v_rcp_f32_e32 v108, v101
	v_add_f32_e32 v101, 1.0, v109
	v_rcp_f32_e32 v99, v99
	v_rcp_f32_e32 v107, v101
	s_mov_b64 s[22:23], 0

.LBB0_433:
	v_cvt_pk_bf16_f32 v82, v92, v94
	v_cvt_pk_bf16_f32 v83, v96, v99
	v_cvt_pk_bf16_f32 v84, v93, v95
	v_cvt_pk_bf16_f32 v85, v97, v98
	global_store_dwordx4 v[90:91], v[82:85], off offset:256
	s_cmp_gt_i32 s15, 2
	s_mov_b64 s[22:23], -1
	v_or_b32_e32 v82, 48, v140
	v_ashrrev_i32_e32 v83, 31, v82
	v_add_f32_e32 v216, v216, v217
	v_add_f32_e32 v218, v218, v219
	v_add_f32_e32 v216, v216, v218
	v_mov_b32_e32 v217, v216
	s_nop 1
	v_permlane16_swap_b32_e32 v216, v217
	v_add_f32_e32 v216, v216, v217
	v_mov_b32_e32 v217, v216
	s_nop 1
	v_permlane32_swap_b32_e32 v216, v217
	v_add_f32_e32 v83, v216, v217
	v_fmamk_f32 v83, v83, 0x3a800000, v161
	v_mul_f32_e32 v84, 0x4b800000, v83
	v_cmp_gt_f32_e32 vcc, s62, v83
	s_nop 1
	v_cndmask_b32_e32 v83, v83, v84, vcc
	v_rsq_f32_e32 v83, v83
	s_nop 0
	v_mul_f32_e32 v84, 0x45800000, v83
	v_cndmask_b32_e32 v83, v83, v84, vcc
	v_mul_f32_e32 v84, 0x3e38aa3b, v83
	v_cndmask_b32_e64 v84, v83, v84, s[10:11]
	v_pk_mul_f32 v[80:81], v[80:81], v[84:85] op_sel_hi:[1,0]
	v_pk_mul_f32 v[78:79], v[78:79], v[84:85] op_sel_hi:[1,0]
	v_pk_mul_f32 v[76:77], v[76:77], v[84:85] op_sel_hi:[1,0]
	v_pk_mul_f32 v[74:75], v[74:75], v[84:85] op_sel_hi:[1,0]
	s_cbranch_scc0 .LBB0_435
	v_mul_f32_e32 v85, 0xbfb8aa3b, v74
	v_exp_f32_e32 v85, v85
	v_mul_f32_e32 v86, 0xbfb8aa3b, v79
	v_exp_f32_e32 v87, v86
	v_mul_f32_e32 v86, 0xbfb8aa3b, v75
	v_exp_f32_e32 v88, v86
	v_add_f32_e32 v85, 1.0, v85
	v_rcp_f32_e32 v86, v85
	v_add_f32_e32 v85, 1.0, v87
	v_rcp_f32_e32 v87, v85
	v_add_f32_e32 v85, 1.0, v88
	v_mul_f32_e32 v88, 0xbfb8aa3b, v80
	v_exp_f32_e32 v89, v88
	v_mul_f32_e32 v88, 0xbfb8aa3b, v76
	v_exp_f32_e32 v90, v88
	v_rcp_f32_e32 v88, v85
	v_add_f32_e32 v85, 1.0, v89
	v_rcp_f32_e32 v89, v85
	v_add_f32_e32 v85, 1.0, v90
	v_mul_f32_e32 v90, 0xbfb8aa3b, v81
	v_mul_f32_e32 v83, 0xbfb8aa3b, v78
	v_exp_f32_e32 v91, v90
	v_mul_f32_e32 v90, 0xbfb8aa3b, v77
	v_exp_f32_e32 v83, v83
	v_exp_f32_e32 v93, v90
	v_rcp_f32_e32 v90, v85
	v_add_f32_e32 v85, 1.0, v91
	v_add_f32_e32 v83, 1.0, v83
	v_rcp_f32_e32 v92, v85
	v_add_f32_e32 v85, 1.0, v93
	v_rcp_f32_e32 v83, v83
	v_rcp_f32_e32 v91, v85
	s_mov_b64 s[22:23], 0

.LBB0_445:
	v_cvt_pk_bf16_f32 v66, v76, v78
	v_cvt_pk_bf16_f32 v67, v80, v83
	v_cvt_pk_bf16_f32 v68, v77, v79
	v_cvt_pk_bf16_f32 v69, v81, v82
	global_store_dwordx4 v[74:75], v[66:69], off offset:256
	s_cmp_gt_i32 s15, 2
	s_mov_b64 s[22:23], -1
	v_add_u32_e32 v66, 0x80, v140
	v_ashrrev_i32_e32 v67, 31, v66
	v_add_f32_e32 v220, v220, v221
	v_add_f32_e32 v222, v222, v223
	v_add_f32_e32 v220, v220, v222
	v_mov_b32_e32 v221, v220
	s_nop 1
	v_permlane16_swap_b32_e32 v220, v221
	v_add_f32_e32 v220, v220, v221
	v_mov_b32_e32 v221, v220
	s_nop 1
	v_permlane32_swap_b32_e32 v220, v221
	v_add_f32_e32 v67, v220, v221
	v_fmamk_f32 v67, v67, 0x3a800000, v161
	v_mul_f32_e32 v68, 0x4b800000, v67
	v_cmp_gt_f32_e32 vcc, s62, v67
	s_nop 1
	v_cndmask_b32_e32 v67, v67, v68, vcc
	v_rsq_f32_e32 v67, v67
	s_nop 0
	v_mul_f32_e32 v68, 0x45800000, v67
	v_cndmask_b32_e32 v67, v67, v68, vcc
	v_mul_f32_e32 v68, 0x3e38aa3b, v67
	v_cndmask_b32_e64 v68, v67, v68, s[10:11]
	v_pk_mul_f32 v[64:65], v[64:65], v[68:69] op_sel_hi:[1,0]
	v_pk_mul_f32 v[62:63], v[62:63], v[68:69] op_sel_hi:[1,0]
	v_pk_mul_f32 v[60:61], v[60:61], v[68:69] op_sel_hi:[1,0]
	v_pk_mul_f32 v[58:59], v[58:59], v[68:69] op_sel_hi:[1,0]
	s_cbranch_scc0 .LBB0_447
	v_mul_f32_e32 v69, 0xbfb8aa3b, v58
	v_exp_f32_e32 v69, v69
	v_mul_f32_e32 v70, 0xbfb8aa3b, v63
	v_exp_f32_e32 v71, v70
	v_mul_f32_e32 v70, 0xbfb8aa3b, v59
	v_exp_f32_e32 v72, v70
	v_add_f32_e32 v69, 1.0, v69
	v_rcp_f32_e32 v70, v69
	v_add_f32_e32 v69, 1.0, v71
	v_rcp_f32_e32 v71, v69
	v_add_f32_e32 v69, 1.0, v72
	v_mul_f32_e32 v72, 0xbfb8aa3b, v64
	v_exp_f32_e32 v73, v72
	v_mul_f32_e32 v72, 0xbfb8aa3b, v60
	v_exp_f32_e32 v74, v72
	v_rcp_f32_e32 v72, v69
	v_add_f32_e32 v69, 1.0, v73
	v_rcp_f32_e32 v73, v69
	v_add_f32_e32 v69, 1.0, v74
	v_mul_f32_e32 v74, 0xbfb8aa3b, v65
	v_mul_f32_e32 v67, 0xbfb8aa3b, v62
	v_exp_f32_e32 v75, v74
	v_mul_f32_e32 v74, 0xbfb8aa3b, v61
	v_exp_f32_e32 v67, v67
	v_exp_f32_e32 v77, v74
	v_rcp_f32_e32 v74, v69
	v_add_f32_e32 v69, 1.0, v75
	v_add_f32_e32 v67, 1.0, v67
	v_rcp_f32_e32 v76, v69
	v_add_f32_e32 v69, 1.0, v77
	v_rcp_f32_e32 v67, v67
	v_rcp_f32_e32 v75, v69
	s_mov_b64 s[22:23], 0

.LBB0_457:
	v_cvt_pk_bf16_f32 v50, v60, v62
	v_cvt_pk_bf16_f32 v51, v64, v67
	v_cvt_pk_bf16_f32 v52, v61, v63
	v_cvt_pk_bf16_f32 v53, v65, v66
	global_store_dwordx4 v[58:59], v[50:53], off offset:256
	s_cmp_gt_i32 s15, 2
	s_mov_b64 s[22:23], -1
	v_add_u32_e32 v50, 0x90, v140
	v_ashrrev_i32_e32 v51, 31, v50
	v_add_f32_e32 v224, v224, v225
	v_add_f32_e32 v226, v226, v227
	v_add_f32_e32 v224, v224, v226
	v_mov_b32_e32 v225, v224
	s_nop 1
	v_permlane16_swap_b32_e32 v224, v225
	v_add_f32_e32 v224, v224, v225
	v_mov_b32_e32 v225, v224
	s_nop 1
	v_permlane32_swap_b32_e32 v224, v225
	v_add_f32_e32 v51, v224, v225
	v_fmamk_f32 v51, v51, 0x3a800000, v161
	v_mul_f32_e32 v52, 0x4b800000, v51
	v_cmp_gt_f32_e32 vcc, s62, v51
	s_nop 1
	v_cndmask_b32_e32 v51, v51, v52, vcc
	v_rsq_f32_e32 v51, v51
	s_nop 0
	v_mul_f32_e32 v52, 0x45800000, v51
	v_cndmask_b32_e32 v51, v51, v52, vcc
	v_mul_f32_e32 v52, 0x3e38aa3b, v51
	v_cndmask_b32_e64 v52, v51, v52, s[10:11]
	v_pk_mul_f32 v[48:49], v[48:49], v[52:53] op_sel_hi:[1,0]
	v_pk_mul_f32 v[46:47], v[46:47], v[52:53] op_sel_hi:[1,0]
	v_pk_mul_f32 v[44:45], v[44:45], v[52:53] op_sel_hi:[1,0]
	v_pk_mul_f32 v[42:43], v[42:43], v[52:53] op_sel_hi:[1,0]
	s_cbranch_scc0 .LBB0_459
	v_mul_f32_e32 v53, 0xbfb8aa3b, v42
	v_exp_f32_e32 v53, v53
	v_mul_f32_e32 v54, 0xbfb8aa3b, v47
	v_exp_f32_e32 v55, v54
	v_mul_f32_e32 v54, 0xbfb8aa3b, v43
	v_exp_f32_e32 v56, v54
	v_add_f32_e32 v53, 1.0, v53
	v_rcp_f32_e32 v54, v53
	v_add_f32_e32 v53, 1.0, v55
	v_rcp_f32_e32 v55, v53
	v_add_f32_e32 v53, 1.0, v56
	v_mul_f32_e32 v56, 0xbfb8aa3b, v48
	v_exp_f32_e32 v57, v56
	v_mul_f32_e32 v56, 0xbfb8aa3b, v44
	v_exp_f32_e32 v58, v56
	v_rcp_f32_e32 v56, v53
	v_add_f32_e32 v53, 1.0, v57
	v_rcp_f32_e32 v57, v53
	v_add_f32_e32 v53, 1.0, v58
	v_mul_f32_e32 v58, 0xbfb8aa3b, v49
	v_mul_f32_e32 v51, 0xbfb8aa3b, v46
	v_exp_f32_e32 v59, v58
	v_mul_f32_e32 v58, 0xbfb8aa3b, v45
	v_exp_f32_e32 v51, v51
	v_exp_f32_e32 v61, v58
	v_rcp_f32_e32 v58, v53
	v_add_f32_e32 v53, 1.0, v59
	v_add_f32_e32 v51, 1.0, v51
	v_rcp_f32_e32 v60, v53
	v_add_f32_e32 v53, 1.0, v61
	v_rcp_f32_e32 v51, v51
	v_rcp_f32_e32 v59, v53
	s_mov_b64 s[22:23], 0

.LBB0_469:
	v_cvt_pk_bf16_f32 v34, v44, v46
	v_cvt_pk_bf16_f32 v35, v48, v51
	v_cvt_pk_bf16_f32 v36, v45, v47
	v_cvt_pk_bf16_f32 v37, v49, v50
	global_store_dwordx4 v[42:43], v[34:37], off offset:256
	s_cmp_gt_i32 s15, 2
	s_mov_b64 s[22:23], -1
	v_add_u32_e32 v34, 0xa0, v140
	v_ashrrev_i32_e32 v35, 31, v34
	v_add_f32_e32 v228, v228, v229
	v_add_f32_e32 v230, v230, v231
	v_add_f32_e32 v228, v228, v230
	v_mov_b32_e32 v229, v228
	s_nop 1
	v_permlane16_swap_b32_e32 v228, v229
	v_add_f32_e32 v228, v228, v229
	v_mov_b32_e32 v229, v228
	s_nop 1
	v_permlane32_swap_b32_e32 v228, v229
	v_add_f32_e32 v35, v228, v229
	v_fmamk_f32 v35, v35, 0x3a800000, v161
	v_mul_f32_e32 v36, 0x4b800000, v35
	v_cmp_gt_f32_e32 vcc, s62, v35
	s_nop 1
	v_cndmask_b32_e32 v35, v35, v36, vcc
	v_rsq_f32_e32 v35, v35
	s_nop 0
	v_mul_f32_e32 v36, 0x45800000, v35
	v_cndmask_b32_e32 v35, v35, v36, vcc
	v_mul_f32_e32 v36, 0x3e38aa3b, v35
	v_cndmask_b32_e64 v36, v35, v36, s[10:11]
	v_pk_mul_f32 v[32:33], v[32:33], v[36:37] op_sel_hi:[1,0]
	v_pk_mul_f32 v[30:31], v[30:31], v[36:37] op_sel_hi:[1,0]
	v_pk_mul_f32 v[28:29], v[28:29], v[36:37] op_sel_hi:[1,0]
	v_pk_mul_f32 v[26:27], v[26:27], v[36:37] op_sel_hi:[1,0]
	s_cbranch_scc0 .LBB0_471
	v_mul_f32_e32 v37, 0xbfb8aa3b, v26
	v_exp_f32_e32 v37, v37
	v_mul_f32_e32 v38, 0xbfb8aa3b, v31
	v_exp_f32_e32 v39, v38
	v_mul_f32_e32 v38, 0xbfb8aa3b, v27
	v_exp_f32_e32 v40, v38
	v_add_f32_e32 v37, 1.0, v37
	v_rcp_f32_e32 v38, v37
	v_add_f32_e32 v37, 1.0, v39
	v_rcp_f32_e32 v39, v37
	v_add_f32_e32 v37, 1.0, v40
	v_mul_f32_e32 v40, 0xbfb8aa3b, v32
	v_exp_f32_e32 v41, v40
	v_mul_f32_e32 v40, 0xbfb8aa3b, v28
	v_exp_f32_e32 v42, v40
	v_rcp_f32_e32 v40, v37
	v_add_f32_e32 v37, 1.0, v41
	v_rcp_f32_e32 v41, v37
	v_add_f32_e32 v37, 1.0, v42
	v_mul_f32_e32 v42, 0xbfb8aa3b, v33
	v_mul_f32_e32 v35, 0xbfb8aa3b, v30
	v_exp_f32_e32 v43, v42
	v_mul_f32_e32 v42, 0xbfb8aa3b, v29
	v_exp_f32_e32 v35, v35
	v_exp_f32_e32 v45, v42
	v_rcp_f32_e32 v42, v37
	v_add_f32_e32 v37, 1.0, v43
	v_add_f32_e32 v35, 1.0, v35
	v_rcp_f32_e32 v44, v37
	v_add_f32_e32 v37, 1.0, v45
	v_rcp_f32_e32 v35, v35
	v_rcp_f32_e32 v43, v37
	s_mov_b64 s[22:23], 0

.LBB0_481:
	v_cvt_pk_bf16_f32 v18, v28, v30
	v_cvt_pk_bf16_f32 v19, v32, v35
	v_cvt_pk_bf16_f32 v20, v29, v31
	v_cvt_pk_bf16_f32 v21, v33, v34
	global_store_dwordx4 v[26:27], v[18:21], off offset:256
	s_cmp_gt_i32 s15, 2
	s_nop 0
	v_add_u32_e32 v18, 0xb0, v140
	v_ashrrev_i32_e32 v19, 31, v18
	v_add_f32_e32 v232, v232, v233
	v_add_f32_e32 v234, v234, v235
	v_add_f32_e32 v232, v232, v234
	v_mov_b32_e32 v233, v232
	s_nop 1
	v_permlane16_swap_b32_e32 v232, v233
	v_add_f32_e32 v232, v232, v233
	v_mov_b32_e32 v233, v232
	s_nop 1
	v_permlane32_swap_b32_e32 v232, v233
	v_add_f32_e32 v19, v232, v233
	v_fmamk_f32 v19, v19, 0x3a800000, v161
	v_mul_f32_e32 v20, 0x4b800000, v19
	v_cmp_gt_f32_e32 vcc, s62, v19
	s_nop 1
	v_cndmask_b32_e32 v19, v19, v20, vcc
	v_rsq_f32_e32 v19, v19
	s_nop 0
	v_mul_f32_e32 v20, 0x45800000, v19
	v_cndmask_b32_e32 v19, v19, v20, vcc
	v_mul_f32_e32 v20, 0x3e38aa3b, v19
	v_cndmask_b32_e64 v20, v19, v20, s[10:11]
	v_pk_mul_f32 v[16:17], v[16:17], v[20:21] op_sel_hi:[1,0]
	v_pk_mul_f32 v[14:15], v[14:15], v[20:21] op_sel_hi:[1,0]
	v_pk_mul_f32 v[12:13], v[12:13], v[20:21] op_sel_hi:[1,0]
	v_pk_mul_f32 v[10:11], v[10:11], v[20:21] op_sel_hi:[1,0]
	s_mov_b64 s[10:11], -1
	s_cbranch_scc0 .LBB0_483
	v_mul_f32_e32 v21, 0xbfb8aa3b, v10
	v_exp_f32_e32 v21, v21
	v_mul_f32_e32 v22, 0xbfb8aa3b, v15
	v_exp_f32_e32 v23, v22
	v_mul_f32_e32 v22, 0xbfb8aa3b, v11
	v_exp_f32_e32 v24, v22
	v_add_f32_e32 v21, 1.0, v21
	v_rcp_f32_e32 v22, v21
	v_add_f32_e32 v21, 1.0, v23
	v_rcp_f32_e32 v23, v21
	v_add_f32_e32 v21, 1.0, v24
	v_mul_f32_e32 v24, 0xbfb8aa3b, v16
	v_exp_f32_e32 v25, v24
	v_mul_f32_e32 v24, 0xbfb8aa3b, v12
	v_exp_f32_e32 v26, v24
	v_rcp_f32_e32 v24, v21
	v_add_f32_e32 v21, 1.0, v25
	v_rcp_f32_e32 v25, v21
	v_add_f32_e32 v21, 1.0, v26
	v_mul_f32_e32 v26, 0xbfb8aa3b, v17
	v_mul_f32_e32 v19, 0xbfb8aa3b, v14
	v_exp_f32_e32 v27, v26
	v_mul_f32_e32 v26, 0xbfb8aa3b, v13
	v_exp_f32_e32 v19, v19
	v_exp_f32_e32 v29, v26
	v_rcp_f32_e32 v26, v21
	v_add_f32_e32 v21, 1.0, v27
	v_add_f32_e32 v19, 1.0, v19
	v_rcp_f32_e32 v28, v21
	v_add_f32_e32 v21, 1.0, v29
	v_rcp_f32_e32 v19, v19
	v_rcp_f32_e32 v27, v21
	s_mov_b64 s[10:11], 0
